# v020: v019 + P4a/P4b skinny epilogue gate/addend loads issued before the LDS reduce (copied into the original registers after vmcnt(0))
# baseline (speedup 1.0000x reference)
; __device__ __forceinline__ float bflo(unsigned w) { return __uint_as_float(w << 16); }
; __device__ __forceinline__ float bfhi(unsigned w) { return __uint_as_float(w & 0xffff0000u); }
; __device__ __forceinline__ u32x2 pack4(const f32x4 v) { u32x2 w; w.x = cvt_pk_bf16(v.x, v.y); w.y = cvt_pk_bf16(v.z, v.w); return w; }
;     __device__ __forceinline__ void apply(int row, int tile, int g, f32x4 v, f32x4) const { *(u32x2*)(O + (size_t)row * D + 16 * tile + 4 * g) = pack4(v); }
; template <class SE> __device__ __forceinline__ void skinny_gemm(const Frame& F, const bf16* Am, const bf16* Bt, int ntiles, int K, const SE& E) {
;     ...
;         part[w * 64 + F.lane] = acc0; if (SE::DUAL) part[512 + w * 64 + F.lane] = acc1;
;         asm volatile("s_waitcnt lgkmcnt(0)" ::: "memory"); __builtin_amdgcn_s_barrier(); asm volatile("" ::: "memory");
;         if (w == 0) {
;             f32x4 t0 = part[F.lane], t1 = {0.f, 0.f, 0.f, 0.f}; if (SE::DUAL) t1 = part[512 + F.lane];
; #pragma unroll
;             for (int ww = 1; ww < 8; ++ww) { t0 += part[ww * 64 + F.lane]; if (SE::DUAL) t1 += part[512 + ww * 64 + F.lane]; }
;             E.apply(MF + j, tile, g, t0, t1);
;     __device__ __forceinline__ void apply(int row, int tile, int g, f32x4 v, f32x4) const {
;         const size_t off = (size_t)row * D + 16 * tile + 4 * g; const u32x2 gg = *(const u32x2*)(G + off);
;         f32x4 o = {bflo(gg.x) * v.x, bfhi(gg.x) * v.y, bflo(gg.y) * v.z, bfhi(gg.y) * v.w};
;         if (ADD) { const u32x2 t = *(const u32x2*)(T + off); o.x += bflo(t.x); o.y += bfhi(t.x); o.z += bflo(t.y); o.w += bfhi(t.y); }
;         *(u32x2*)(O + off) = pack4(o);
.LBB0_613:
	ds_write_b128 v76, v[64:67]
	s_waitcnt lgkmcnt(0)
	s_barrier
	s_and_b64 vcc, exec, s[10:11]
	s_cbranch_vccz .LBB0_576
	ds_read_b128 v[64:67], v151
	ds_read_b128 v[78:81], v151 offset:1024
	ds_read_b128 v[100:103], v151 offset:2048
	ds_read_b128 v[104:107], v151 offset:3072
	ds_read_b128 v[108:111], v151 offset:4096
	ds_read_b128 v[112:115], v151 offset:5120
	ds_read_b128 v[116:119], v151 offset:6144
	ds_read_b128 v[120:123], v151 offset:7168
	s_ashr_i32 s15, s14, 31
	v_lshl_add_u64 v[124:125], s[14:15], 0, v[72:73]
	v_lshlrev_b64 v[124:125], 1, v[124:125]
	v_lshl_add_u64 v[124:125], s[8:9], 0, v[124:125]
	global_load_dwordx2 v[126:127], v[124:125], off
	s_waitcnt lgkmcnt(6)
	v_pk_add_f32 v[74:75], v[66:67], v[80:81]
	v_pk_add_f32 v[78:79], v[64:65], v[78:79]
	s_waitcnt lgkmcnt(5)
	v_pk_add_f32 v[74:75], v[74:75], v[102:103]
	v_pk_add_f32 v[78:79], v[78:79], v[100:101]
	s_waitcnt lgkmcnt(4)
	v_pk_add_f32 v[74:75], v[74:75], v[106:107]
	v_pk_add_f32 v[78:79], v[78:79], v[104:105]
	s_waitcnt lgkmcnt(3)
	v_pk_add_f32 v[74:75], v[74:75], v[110:111]
	v_pk_add_f32 v[78:79], v[78:79], v[108:109]
	s_waitcnt lgkmcnt(2)
	v_pk_add_f32 v[74:75], v[74:75], v[114:115]
	v_pk_add_f32 v[78:79], v[78:79], v[112:113]
	s_waitcnt lgkmcnt(1)
	v_pk_add_f32 v[74:75], v[74:75], v[118:119]
	v_pk_add_f32 v[78:79], v[78:79], v[116:117]
	s_waitcnt lgkmcnt(0)
	v_pk_add_f32 v[66:67], v[74:75], v[122:123]
	v_lshl_add_u64 v[74:75], s[14:15], 0, v[72:73]
	v_lshlrev_b64 v[74:75], 1, v[74:75]
	v_pk_add_f32 v[64:65], v[78:79], v[120:121]
	s_waitcnt vmcnt(0)
	v_mov_b64_e32 v[78:79], v[126:127]
	v_lshlrev_b32_e32 v80, 16, v78
	v_and_b32_e32 v81, 0xffff0000, v78
	v_lshlrev_b32_e32 v78, 16, v79
	v_and_b32_e32 v79, 0xffff0000, v79
	v_pk_mul_f32 v[64:65], v[64:65], v[80:81]
	v_pk_mul_f32 v[66:67], v[66:67], v[78:79]
	v_cvt_pk_bf16_f32 v64, v64, v65
	v_cvt_pk_bf16_f32 v65, v66, v67
	v_lshl_add_u64 v[66:67], s[2:3], 0, v[74:75]
	global_store_dwordx2 v[66:67], v[64:65], off
	s_branch .LBB0_576

; __device__ __forceinline__ float bflo(unsigned w) { return __uint_as_float(w << 16); }
; __device__ __forceinline__ float bfhi(unsigned w) { return __uint_as_float(w & 0xffff0000u); }
; __device__ __forceinline__ u32x2 pack4(const f32x4 v) { u32x2 w; w.x = cvt_pk_bf16(v.x, v.y); w.y = cvt_pk_bf16(v.z, v.w); return w; }
;     __device__ __forceinline__ void apply(int row, int tile, int g, f32x4 v, f32x4) const { *(u32x2*)(O + (size_t)row * D + 16 * tile + 4 * g) = pack4(v); }
; template <class SE> __device__ __forceinline__ void skinny_gemm(const Frame& F, const bf16* Am, const bf16* Bt, int ntiles, int K, const SE& E) {
;     ...
;         part[w * 64 + F.lane] = acc0; if (SE::DUAL) part[512 + w * 64 + F.lane] = acc1;
;         asm volatile("s_waitcnt lgkmcnt(0)" ::: "memory"); __builtin_amdgcn_s_barrier(); asm volatile("" ::: "memory");
;         if (w == 0) {
;             f32x4 t0 = part[F.lane], t1 = {0.f, 0.f, 0.f, 0.f}; if (SE::DUAL) t1 = part[512 + F.lane];
; #pragma unroll
;             for (int ww = 1; ww < 8; ++ww) { t0 += part[ww * 64 + F.lane]; if (SE::DUAL) t1 += part[512 + ww * 64 + F.lane]; }
;             E.apply(MF + j, tile, g, t0, t1);
;     __device__ __forceinline__ void apply(int row, int tile, int g, f32x4 v, f32x4) const {
;         const size_t off = (size_t)row * D + 16 * tile + 4 * g; const u32x2 gg = *(const u32x2*)(G + off);
;         f32x4 o = {bflo(gg.x) * v.x, bfhi(gg.x) * v.y, bflo(gg.y) * v.z, bfhi(gg.y) * v.w};
;         if (ADD) { const u32x2 t = *(const u32x2*)(T + off); o.x += bflo(t.x); o.y += bfhi(t.x); o.z += bflo(t.y); o.w += bfhi(t.y); }
;         *(u32x2*)(O + off) = pack4(o);
.LBB0_678:
	ds_write_b128 v76, v[64:67]
	s_waitcnt lgkmcnt(0)
	s_barrier
	s_and_b64 vcc, exec, s[4:5]
	s_cbranch_vccz .LBB0_641
	ds_read_b128 v[64:67], v151
	ds_read_b128 v[78:81], v151 offset:1024
	ds_read_b128 v[100:103], v151 offset:2048
	ds_read_b128 v[104:107], v151 offset:3072
	ds_read_b128 v[108:111], v151 offset:4096
	ds_read_b128 v[112:115], v151 offset:5120
	ds_read_b128 v[116:119], v151 offset:6144
	ds_read_b128 v[120:123], v151 offset:7168
	s_ashr_i32 s7, s6, 31
	v_lshl_add_u64 v[124:125], s[6:7], 0, v[72:73]
	v_lshlrev_b64 v[124:125], 1, v[124:125]
	v_lshl_add_u64 v[128:129], s[2:3], 0, v[124:125]
	v_lshl_add_u64 v[124:125], s[8:9], 0, v[124:125]
	global_load_dwordx2 v[126:127], v[124:125], off
	global_load_dwordx2 v[128:129], v[128:129], off
	s_waitcnt lgkmcnt(6)
	v_pk_add_f32 v[74:75], v[66:67], v[80:81]
	v_pk_add_f32 v[78:79], v[64:65], v[78:79]
	s_waitcnt lgkmcnt(5)
	v_pk_add_f32 v[74:75], v[74:75], v[102:103]
	v_pk_add_f32 v[78:79], v[78:79], v[100:101]
	s_waitcnt lgkmcnt(4)
	v_pk_add_f32 v[74:75], v[74:75], v[106:107]
	v_pk_add_f32 v[78:79], v[78:79], v[104:105]
	s_waitcnt lgkmcnt(3)
	v_pk_add_f32 v[74:75], v[74:75], v[110:111]
	v_pk_add_f32 v[78:79], v[78:79], v[108:109]
	s_waitcnt lgkmcnt(2)
	v_pk_add_f32 v[74:75], v[74:75], v[114:115]
	v_pk_add_f32 v[78:79], v[78:79], v[112:113]
	s_waitcnt lgkmcnt(1)
	v_pk_add_f32 v[74:75], v[74:75], v[118:119]
	v_pk_add_f32 v[78:79], v[78:79], v[116:117]
	s_waitcnt lgkmcnt(0)
	v_pk_add_f32 v[66:67], v[74:75], v[122:123]
	v_lshl_add_u64 v[74:75], s[6:7], 0, v[72:73]
	v_lshlrev_b64 v[74:75], 1, v[74:75]
	v_pk_add_f32 v[64:65], v[78:79], v[120:121]
	s_waitcnt vmcnt(0)
	v_mov_b64_e32 v[78:79], v[126:127]
	v_mov_b64_e32 v[80:81], v[128:129]
	v_lshlrev_b32_e32 v82, 16, v78
	v_and_b32_e32 v83, 0xffff0000, v78
	s_waitcnt vmcnt(0)
	v_lshlrev_b32_e32 v84, 16, v80
	v_and_b32_e32 v85, 0xffff0000, v80
	v_lshlrev_b32_e32 v78, 16, v79
	v_and_b32_e32 v79, 0xffff0000, v79
	v_lshlrev_b32_e32 v80, 16, v81
	v_and_b32_e32 v81, 0xffff0000, v81
	v_pk_fma_f32 v[64:65], v[64:65], v[82:83], v[84:85]
	v_pk_fma_f32 v[66:67], v[66:67], v[78:79], v[80:81]
	v_cvt_pk_bf16_f32 v64, v64, v65
	v_cvt_pk_bf16_f32 v65, v66, v67
	v_lshl_add_u64 v[66:67], s[10:11], 0, v[74:75]
	global_store_dwordx2 v[66:67], v[64:65], off
	s_branch .LBB0_641
